# NA unit prologue: 8 Q loads issued together with counted waits (on v28)
# speedup vs baseline: 1.0074x; 1.0074x over previous
; __device__ __forceinline__ int opaque_tid() { int t = threadIdx.x; asm volatile("" : "+v"(t)); return t; }
; __device__ __forceinline__ float bf2f(unsigned h) { return __uint_as_float(h << 16); }
; __device__ __forceinline__ void na_unit3(char* lds, const bf16_t* __restrict__ Qp, const bf16_t* __restrict__ Knp, const bf16_t* __restrict__ Vp, ...
;     ...
;   const int tid = opaque_tid(), wid = __builtin_amdgcn_readfirstlane(tid >> 6), lane = tid & 63, r32 = lane & 31, hi = lane >> 5;
;   float* wsf = (float*)(lds + N_WS) + wid * 64; float* li_l = wsf; float* al_l = wsf + 32;
;   float* tab = (float*)(lds + N_TAB) + 256;
;   const unsigned lds0 = (unsigned)(uintptr_t)lds;
;   const int pk = (wid & 3) + 8 * (wid >> 2);
;   const int krow_n = 4 * pk + (lane >> 4);
;   const unsigned kn_off = (unsigned)(krow_n * LDK + (((lane & 15) ^ (krow_n & 15)) << 3)) * 2u;
;   const int vst_ = 2 * wid + (lane >> 5), vkk = (vst_ >> 2) * 8 + ((lane >> 2) & 7), vkey = (vkk & ~0xC) | ((vkk & 4) << 1) | ((vkk & 8) >> 1), vcol = (vst_ & 3) * 32 + (lane & 3) * 8;
;   const unsigned v_off = (unsigned)(vkey * LDK + vcol) * 2u;
;   const unsigned kn_dst = lds0 + N_KN + pk * 1024, v_dst = lds0 + N_V + wid * 1024;
;     ...
;   DMA_T(0, 0); DMA_T(1, 1); DMA_T(2, 2);
;   float l_reg = 0.f; f32x16 o[4] = {}; bf16x8 qr[8];
;   const bf16_t* Qw = Qp + (long)(wid * QBLK + r32) * LDQ + hi * 8;
; #pragma unroll
;   for (int d0 = 0; d0 < 8; ++d0) { const u32x4 raw = *reinterpret_cast<const u32x4*>(Qw + d0 * 16); u32x4 w;
; #pragma unroll
;     for (int p = 0; p < 4; ++p) w[p] = cvtpk(bf2f(raw[p] & 0xffffu) * C, bf2f(raw[p] >> 16) * C);
;     qr[d0] = *reinterpret_cast<bf16x8*>(&w); }
; __global__ void __launch_bounds__(NWAVES * 64, 2) fwd_mega(Args args) {
;     ...
;                 const int bh = u >> 5, rg = u & 31, b = bh >> 4, h = bh & 15, r0row = rg * 4;
;                 const int R0 = min(max(r0row - 4, 0), 120), last = min(max(r0row - 1, 0), 120) + 7, NT = last - R0 + 1;
;                 const size_t tok0 = (size_t)b * SEQ + r0row * 64, key0 = (size_t)b * SEQ + R0 * 64;
;                 const size_t TS = (size_t)M_TOK * 256; const bf16_t* hb = QKVZ + (size_t)(h >> 1) * TS + (h & 1) * 128;
;                 att::na_unit3((char*)lds, hb + tok0 * 256, hb + 8 * TS + key0 * 256, hb + 16 * TS + key0 * 256,
.LBB0_276:
	s_lshl_b32 s1, s76, 2
	s_ashr_i32 s30, s76, 9
	s_and_b32 s1, s1, 0x7c
	v_sub_u32_e64 v1, s1, 4 clamp
	s_ashr_i32 s31, s30, 31
	v_readfirstlane_b32 s85, v1
	s_lshl_b64 s[8:9], s[30:31], 13
	s_lshl_b32 s5, s1, 6
	s_or_b32 s34, s8, s5
	s_lshl_b32 s5, s85, 6
	s_or_b32 s8, s8, s5
	s_lshl_b32 s5, s76, 17
	s_lshr_b32 s0, s76, 5
	s_bfe_u32 s77, s76, 0x40005
	s_and_b32 s5, s5, 0x3800000
	s_add_u32 s5, s90, s5
	s_addc_u32 s6, s91, 0
	s_lshl_b32 s7, s76, 3
	s_and_b32 s7, s7, 0x100
	s_mov_b32 s35, s9
	s_add_u32 s81, s5, s7
	s_addc_u32 s84, s6, 0
	s_lshl_b64 s[6:7], s[34:35], 9
	s_add_u32 s6, s81, s6
	s_addc_u32 s7, s84, s7
	s_lshl_b64 s[8:9], s[8:9], 9
	s_add_u32 s5, s81, s8
	s_addc_u32 s14, s84, s9
	s_add_u32 s64, s5, 0x4000000
	s_addc_u32 s65, s14, 0
	v_mov_b32_e32 v2, v252
	s_add_u32 s78, s5, 0x8000000
	s_addc_u32 s79, s14, 0
	v_readfirstlane_b32 s10, v2
	s_ashr_i32 s15, s10, 6
	s_ashr_i32 s9, s10, 5
	s_and_b32 s8, s15, 3
	s_and_b32 s9, s9, -8
	s_or_b32 s8, s8, s9
	s_lshl_b32 s9, s8, 2
	v_bfe_u32 v1, v2, 4, 2
	v_or_b32_e32 v3, s9, v1
	v_bitop3_b32 v1, s9, v2, v1 bitop3:0x36
	s_ashr_i32 s12, s10, 4
	v_lshlrev_b32_e32 v3, 9, v3
	v_lshlrev_b32_e32 v1, 4, v1
	s_and_b32 s13, s12, 0x7ffff0
	s_lshr_b32 s12, s12, 1
	v_and_or_b32 v223, v1, s53, v3
	s_lshl_b32 s9, s15, 1
	v_lshrrev_b32_e32 v1, 2, v2
	v_lshrrev_b32_e32 v3, 1, v2
	s_and_b32 s12, s12, 4
	s_lshl_b32 s8, s8, 10
	v_bfe_u32 v222, v2, 5, 1
	v_and_or_b32 v1, v1, 3, s13
	v_and_b32_e32 v3, 8, v3
	s_cmp_lg_u32 0, -1
	v_or3_b32 v1, v1, v3, s12
	v_and_or_b32 v3, s9, 2, v222
	s_cselect_b32 s9, 0, 0
	s_add_i32 s16, s9, s8
	s_lshl_b32 s89, s15, 10
	v_lshlrev_b32_e32 v18, 4, v2
	s_add_i32 s88, s16, 0x10000
	s_add_i32 s89, s89, s9
	s_mov_b32 s8, m0
	s_mov_b32 m0, s88
	s_nop 0
	global_load_lds_dwordx4 v223, s[64:65]
	s_mov_b32 m0, s8
	v_and_b32_e32 v4, 48, v18
	s_add_u32 s8, s5, 0x4002000
	v_lshl_or_b32 v3, v3, 6, v4
	s_addc_u32 s9, s14, 0
	s_add_i32 s12, s88, 0x1000
	s_mov_b32 s13, m0
	s_mov_b32 m0, s12
	s_nop 0
	global_load_lds_dwordx4 v223, s[8:9]
	s_mov_b32 m0, s13
	v_lshl_or_b32 v224, v1, 9, v3
	s_mov_b32 s8, m0
	s_mov_b32 m0, s89
	s_nop 0
	global_load_lds_dwordx4 v224, s[78:79]
	s_mov_b32 m0, s8
	s_add_u32 s8, s5, 0x8004000
	s_addc_u32 s9, s14, 0
	s_add_i32 s12, s89, 0x2000
	s_mov_b32 s13, m0
	s_mov_b32 m0, s12
	s_nop 0
	global_load_lds_dwordx4 v224, s[8:9]
	s_mov_b32 m0, s13
	s_add_u32 s8, s5, 0x4008000
	s_addc_u32 s9, s14, 0
	s_add_u32 s12, s5, 0x8008000
	s_addc_u32 s13, s14, 0
	s_add_i32 s17, s16, 0x14000
	s_add_i32 s18, s89, 0x4000
	s_mov_b32 s19, m0
	s_mov_b32 m0, s17
	s_nop 0
	global_load_lds_dwordx4 v223, s[8:9]
	s_mov_b32 m0, s19
	s_add_u32 s8, s5, 0x400a000
	s_addc_u32 s9, s14, 0
	s_add_i32 s17, s16, 0x15000
	s_mov_b32 s19, m0
	s_mov_b32 m0, s17
	s_nop 0
	global_load_lds_dwordx4 v223, s[8:9]
	s_mov_b32 m0, s19
	s_mov_b32 s8, m0
	s_mov_b32 m0, s18
	s_nop 0
	global_load_lds_dwordx4 v224, s[12:13]
	s_mov_b32 m0, s8
	s_add_u32 s8, s5, 0x800c000
	s_addc_u32 s9, s14, 0
	s_add_i32 s12, s89, 0x6000
	s_mov_b32 s13, m0
	s_mov_b32 m0, s12
	s_nop 0
	global_load_lds_dwordx4 v224, s[8:9]
	s_mov_b32 m0, s13
	s_add_u32 s8, s5, 0x4010000
	s_addc_u32 s9, s14, 0
	s_add_u32 s12, s5, 0x8010000
	s_addc_u32 s13, s14, 0
	s_add_i32 s17, s16, 0x18000
	s_add_i32 s18, s89, 0x8000
	s_mov_b32 s19, m0
	s_mov_b32 m0, s17
	s_nop 0
	global_load_lds_dwordx4 v223, s[8:9]
	s_mov_b32 m0, s19
	s_add_u32 s8, s5, 0x4012000
	s_addc_u32 s9, s14, 0
	s_add_i32 s16, s16, 0x19000
	s_mov_b32 s17, m0
	s_mov_b32 m0, s16
	s_nop 0
	global_load_lds_dwordx4 v223, s[8:9]
	s_mov_b32 m0, s17
	s_mov_b32 s8, m0
	s_mov_b32 m0, s18
	s_nop 0
	global_load_lds_dwordx4 v224, s[12:13]
	s_mov_b32 m0, s8
	s_add_u32 s8, s5, 0x8014000
	v_and_b32_e32 v221, 31, v2
	s_addc_u32 s9, s14, 0
	s_lshl_b32 s80, s15, 5
	v_or_b32_e32 v4, s80, v221
	v_ashrrev_i32_e32 v5, 31, v4
	v_lshlrev_b64 v[4:5], 9, v[4:5]
	v_lshl_add_u64 v[4:5], s[6:7], 0, v[4:5]
	v_lshlrev_b32_e32 v204, 4, v222
	v_mov_b32_e32 v205, v0
	s_add_i32 s5, s89, 0xa000
	s_mov_b32 s12, m0
	s_mov_b32 m0, s5
	s_nop 0
	global_load_lds_dwordx4 v224, s[8:9]
	s_mov_b32 m0, s12
	v_lshl_add_u64 v[8:9], v[4:5], 0, v[204:205]
	global_load_dwordx4 v[160:163], v[8:9], off
	global_load_dwordx4 v[164:167], v[8:9], off offset:32
	global_load_dwordx4 v[168:171], v[8:9], off offset:64
	global_load_dwordx4 v[172:175], v[8:9], off offset:96
	global_load_dwordx4 v[176:179], v[8:9], off offset:128
	global_load_dwordx4 v[180:183], v[8:9], off offset:160
	global_load_dwordx4 v[184:187], v[8:9], off offset:192
	global_load_dwordx4 v[188:191], v[8:9], off offset:224
	s_movk_i32 s5, 0x1d1
	v_cmp_gt_i32_e32 vcc, s5, v2
	s_waitcnt vmcnt(7)
	v_lshlrev_b32_e32 v1, 16, v160
	v_and_b32_e32 v3, 0xffff0000, v160
	v_mul_f32_e32 v1, 0x3e0293ee, v1
	v_mul_f32_e32 v3, 0x3e0293ee, v3
	v_cvt_pk_bf16_f32 v160, v1, v3
	v_and_b32_e32 v1, 0xffff0000, v162
	v_lshlrev_b32_e32 v4, 16, v161
	v_and_b32_e32 v5, 0xffff0000, v161
	v_lshlrev_b32_e32 v10, 16, v162
	v_mul_f32_e32 v1, 0x3e0293ee, v1
	v_mul_f32_e32 v4, 0x3e0293ee, v4
	v_mul_f32_e32 v5, 0x3e0293ee, v5
	v_mul_f32_e32 v10, 0x3e0293ee, v10
	v_cvt_pk_bf16_f32 v161, v4, v5
	v_cvt_pk_bf16_f32 v162, v10, v1
	v_lshlrev_b32_e32 v1, 16, v163
	v_and_b32_e32 v3, 0xffff0000, v163
	v_mul_f32_e32 v1, 0x3e0293ee, v1
	v_mul_f32_e32 v3, 0x3e0293ee, v3
	v_cvt_pk_bf16_f32 v163, v1, v3
	s_waitcnt vmcnt(6)
; __device__ __forceinline__ float bf2f(unsigned h) { return __uint_as_float(h << 16); }
; __device__ __forceinline__ void na_unit3(char* lds, const bf16_t* __restrict__ Qp, const bf16_t* __restrict__ Knp, const bf16_t* __restrict__ Vp, ...
;     ...
;   for (int d0 = 0; d0 < 8; ++d0) { const u32x4 raw = *reinterpret_cast<const u32x4*>(Qw + d0 * 16); u32x4 w;
; #pragma unroll
;     for (int p = 0; p < 4; ++p) w[p] = cvtpk(bf2f(raw[p] & 0xffffu) * C, bf2f(raw[p] >> 16) * C);
;     qr[d0] = *reinterpret_cast<bf16x8*>(&w); }
;   for (int i = tid; i < 15 * 31; i += NW * 64) tab[i] = rpb_h[i] * 1.4426950408889634f;
	v_lshlrev_b32_e32 v1, 16, v164
	v_and_b32_e32 v3, 0xffff0000, v164
	v_lshlrev_b32_e32 v4, 16, v165
	v_and_b32_e32 v5, 0xffff0000, v165
	v_lshlrev_b32_e32 v10, 16, v166
	v_and_b32_e32 v6, 0xffff0000, v166
	v_lshlrev_b32_e32 v11, 16, v167
	v_and_b32_e32 v7, 0xffff0000, v167
	v_mul_f32_e32 v4, 0x3e0293ee, v4
	v_mul_f32_e32 v5, 0x3e0293ee, v5
	v_mul_f32_e32 v6, 0x3e0293ee, v6
	v_mul_f32_e32 v7, 0x3e0293ee, v7
	v_mul_f32_e32 v1, 0x3e0293ee, v1
	v_mul_f32_e32 v3, 0x3e0293ee, v3
	v_mul_f32_e32 v10, 0x3e0293ee, v10
	v_mul_f32_e32 v11, 0x3e0293ee, v11
	v_cvt_pk_bf16_f32 v164, v1, v3
	v_cvt_pk_bf16_f32 v165, v4, v5
	v_cvt_pk_bf16_f32 v166, v10, v6
	v_cvt_pk_bf16_f32 v167, v11, v7
	s_waitcnt vmcnt(5)
	v_lshlrev_b32_e32 v1, 16, v168
	v_and_b32_e32 v3, 0xffff0000, v168
	v_lshlrev_b32_e32 v4, 16, v169
	v_and_b32_e32 v5, 0xffff0000, v169
	v_lshlrev_b32_e32 v10, 16, v170
	v_and_b32_e32 v6, 0xffff0000, v170
	v_lshlrev_b32_e32 v11, 16, v171
	v_and_b32_e32 v7, 0xffff0000, v171
	v_mul_f32_e32 v4, 0x3e0293ee, v4
	v_mul_f32_e32 v5, 0x3e0293ee, v5
	v_mul_f32_e32 v6, 0x3e0293ee, v6
	v_mul_f32_e32 v7, 0x3e0293ee, v7
	v_mul_f32_e32 v1, 0x3e0293ee, v1
	v_mul_f32_e32 v3, 0x3e0293ee, v3
	v_mul_f32_e32 v10, 0x3e0293ee, v10
	v_mul_f32_e32 v11, 0x3e0293ee, v11
	v_cvt_pk_bf16_f32 v168, v1, v3
	v_cvt_pk_bf16_f32 v169, v4, v5
	v_cvt_pk_bf16_f32 v170, v10, v6
	v_cvt_pk_bf16_f32 v171, v11, v7
	s_waitcnt vmcnt(4)
	v_lshlrev_b32_e32 v1, 16, v172
	v_and_b32_e32 v3, 0xffff0000, v172
	v_lshlrev_b32_e32 v4, 16, v173
	v_and_b32_e32 v5, 0xffff0000, v173
	v_lshlrev_b32_e32 v10, 16, v174
	v_and_b32_e32 v6, 0xffff0000, v174
	v_lshlrev_b32_e32 v11, 16, v175
	v_and_b32_e32 v7, 0xffff0000, v175
	v_mul_f32_e32 v4, 0x3e0293ee, v4
	v_mul_f32_e32 v5, 0x3e0293ee, v5
	v_mul_f32_e32 v6, 0x3e0293ee, v6
	v_mul_f32_e32 v7, 0x3e0293ee, v7
	v_mul_f32_e32 v1, 0x3e0293ee, v1
	v_mul_f32_e32 v3, 0x3e0293ee, v3
	v_mul_f32_e32 v10, 0x3e0293ee, v10
	v_mul_f32_e32 v11, 0x3e0293ee, v11
	v_cvt_pk_bf16_f32 v172, v1, v3
	v_cvt_pk_bf16_f32 v173, v4, v5
	v_cvt_pk_bf16_f32 v174, v10, v6
	v_cvt_pk_bf16_f32 v175, v11, v7
	s_waitcnt vmcnt(3)
	v_lshlrev_b32_e32 v1, 16, v176
	v_and_b32_e32 v3, 0xffff0000, v176
	v_lshlrev_b32_e32 v4, 16, v177
	v_and_b32_e32 v5, 0xffff0000, v177
	v_lshlrev_b32_e32 v10, 16, v178
	v_and_b32_e32 v6, 0xffff0000, v178
	v_lshlrev_b32_e32 v11, 16, v179
	v_and_b32_e32 v7, 0xffff0000, v179
	v_mul_f32_e32 v4, 0x3e0293ee, v4
	v_mul_f32_e32 v5, 0x3e0293ee, v5
	v_mul_f32_e32 v6, 0x3e0293ee, v6
	v_mul_f32_e32 v7, 0x3e0293ee, v7
	v_mul_f32_e32 v1, 0x3e0293ee, v1
	v_mul_f32_e32 v3, 0x3e0293ee, v3
	v_mul_f32_e32 v10, 0x3e0293ee, v10
	v_mul_f32_e32 v11, 0x3e0293ee, v11
	v_cvt_pk_bf16_f32 v176, v1, v3
	v_cvt_pk_bf16_f32 v177, v4, v5
	v_cvt_pk_bf16_f32 v178, v10, v6
	v_cvt_pk_bf16_f32 v179, v11, v7
	s_waitcnt vmcnt(2)
	v_lshlrev_b32_e32 v1, 16, v180
	v_and_b32_e32 v3, 0xffff0000, v180
	v_lshlrev_b32_e32 v4, 16, v181
	v_and_b32_e32 v5, 0xffff0000, v181
	v_lshlrev_b32_e32 v10, 16, v182
	v_and_b32_e32 v6, 0xffff0000, v182
	v_lshlrev_b32_e32 v11, 16, v183
	v_and_b32_e32 v7, 0xffff0000, v183
	v_mul_f32_e32 v4, 0x3e0293ee, v4
	v_mul_f32_e32 v5, 0x3e0293ee, v5
	v_mul_f32_e32 v6, 0x3e0293ee, v6
	v_mul_f32_e32 v7, 0x3e0293ee, v7
	v_mul_f32_e32 v1, 0x3e0293ee, v1
	v_mul_f32_e32 v3, 0x3e0293ee, v3
	v_mul_f32_e32 v10, 0x3e0293ee, v10
	v_mul_f32_e32 v11, 0x3e0293ee, v11
	v_cvt_pk_bf16_f32 v180, v1, v3
	v_cvt_pk_bf16_f32 v181, v4, v5
	v_cvt_pk_bf16_f32 v182, v10, v6
	v_cvt_pk_bf16_f32 v183, v11, v7
	s_waitcnt vmcnt(1)
	v_lshlrev_b32_e32 v1, 16, v184
	v_and_b32_e32 v3, 0xffff0000, v184
	v_lshlrev_b32_e32 v4, 16, v185
	v_and_b32_e32 v5, 0xffff0000, v185
	v_lshlrev_b32_e32 v10, 16, v186
	v_and_b32_e32 v6, 0xffff0000, v186
	v_lshlrev_b32_e32 v11, 16, v187
	v_and_b32_e32 v7, 0xffff0000, v187
	v_mul_f32_e32 v4, 0x3e0293ee, v4
	v_mul_f32_e32 v5, 0x3e0293ee, v5
	v_mul_f32_e32 v6, 0x3e0293ee, v6
	v_mul_f32_e32 v7, 0x3e0293ee, v7
	v_mul_f32_e32 v1, 0x3e0293ee, v1
	v_mul_f32_e32 v3, 0x3e0293ee, v3
	v_mul_f32_e32 v10, 0x3e0293ee, v10
	v_mul_f32_e32 v11, 0x3e0293ee, v11
	v_cvt_pk_bf16_f32 v184, v1, v3
	v_cvt_pk_bf16_f32 v185, v4, v5
	v_cvt_pk_bf16_f32 v186, v10, v6
	v_cvt_pk_bf16_f32 v187, v11, v7
	s_waitcnt vmcnt(0)
	v_lshlrev_b32_e32 v1, 16, v188
	v_and_b32_e32 v3, 0xffff0000, v188
	v_lshlrev_b32_e32 v4, 16, v189
	v_and_b32_e32 v5, 0xffff0000, v189
	v_lshlrev_b32_e32 v8, 16, v190
	v_and_b32_e32 v6, 0xffff0000, v190
	v_lshlrev_b32_e32 v9, 16, v191
	v_and_b32_e32 v7, 0xffff0000, v191
	v_mul_f32_e32 v1, 0x3e0293ee, v1
	v_mul_f32_e32 v3, 0x3e0293ee, v3
	v_mul_f32_e32 v4, 0x3e0293ee, v4
	v_mul_f32_e32 v5, 0x3e0293ee, v5
	v_mul_f32_e32 v8, 0x3e0293ee, v8
	v_mul_f32_e32 v6, 0x3e0293ee, v6
	v_mul_f32_e32 v9, 0x3e0293ee, v9
	v_mul_f32_e32 v7, 0x3e0293ee, v7
	v_cvt_pk_bf16_f32 v188, v1, v3
	v_cvt_pk_bf16_f32 v189, v4, v5
	v_cvt_pk_bf16_f32 v190, v8, v6
	v_cvt_pk_bf16_f32 v191, v9, v7
	s_and_saveexec_b64 s[6:7], vcc
	s_cbranch_execz .LBB0_284
	v_max_i32_e32 v1, 0xffffffd1, v2
	v_sub_u32_e32 v1, v1, v2
	v_add_u32_e32 v1, 0x1ff, v1
	s_movk_i32 s5, 0x1ff
	v_cmp_lt_u32_e32 vcc, s5, v1
	s_mov_b64 s[26:27], -1
	v_mov_b32_e32 v4, v2
	s_and_saveexec_b64 s[8:9], vcc
	s_cbranch_execz .LBB0_281
	v_lshrrev_b32_e32 v1, 9, v1
	s_or_b32 s5, s77, s20
	v_readlane_b32 s12, v255, 0
	v_add_u32_e32 v1, 1, v1
	s_mulk_i32 s5, 0x744
	v_readlane_b32 s14, v255, 2
	v_readlane_b32 s15, v255, 3
	s_add_u32 s26, s14, s5
	v_and_b32_e32 v6, 0xfffffe, v1
	v_add_u32_e32 v3, 0x200, v2
	v_readlane_b32 s5, v254, 27
	s_addc_u32 s27, s15, 0
	s_mov_b64 s[36:37], 0
	v_lshl_add_u32 v7, v2, 2, s5
	v_mov_b32_e32 v8, v6
	v_mov_b64_e32 v[4:5], v[2:3]
	v_readlane_b32 s13, v255, 1
	v_readlane_b32 s16, v255, 4
	v_readlane_b32 s17, v255, 5
	v_readlane_b32 s18, v255, 6
	v_readlane_b32 s19, v255, 7
